# k18_gload
# speedup vs baseline: 1.1091x; 1.0037x over previous
; DI f32x16 fzero() { f32x16 z; for (int i = 0; i < 16; ++i) z[i] = 0.f; return z; }
; template <bool MLA>
; DI void attn_task(const Params& p, char* smem, int b, int head, int qt) {
;     ...
;   const int kvh = head >> 2;
;   const int q0 = qt * 128;
;   const int wq0 = q0 + wave * 32;
;   const int qrow = wq0 + r;
;   const int qrow_c = qrow < LT ? qrow : LT - 1;
;   const u16* qp = MLA ? qmla + (size_t)(b * LT + qrow_c) * 768 + head * 96 : proj0 + (size_t)(b * LT + qrow_c) * 1440 + head * 64;
;   bf16x8 qf[NKS];
; #pragma unroll
;   for (int ks = 0; ks < NKS; ++ks) qf[ks] = *(const bf16x8*)(qp + ks * 16 + h * 8);
;   f32x16 oacc[2];
;   oacc[0] = fzero(); oacc[1] = fzero();
;   float m = -1e30f, l = 0.f;
;   const int klo = MLA ? 0 : (q0 >= 127 ? (q0 - 127) / 64 : 0);
;   const int qmax = (q0 + 127 < LT - 1) ? q0 + 127 : LT - 1;
;   const int khi = qmax / 64;
;   constexpr int NKC = (64 * (DQK / 8)) / 256;
;   u32x4 kreg[NKC], vreg[2];
;   auto gload = [&](int kt_) {
;     const int kb = kt_ * 64;
; #pragma unroll
;     for (int i = 0; i < NKC; ++i) {
;       const int c = tid + 256 * i;
;       const int row = c / (DQK / 8), ch = c % (DQK / 8);
;       const int key = (kb + row < LT) ? kb + row : LT - 1;
;       const size_t grow = (size_t)b * LT + key;
;       if (MLA) kreg[i] = ch < 8 ? *(const u32x4*)(kvmla + grow * 1024 + head * 128 + ch * 8) : *(const u32x4*)(krope + grow * 32 + (ch - 8) * 8);
;       else kreg[i] = *(const u32x4*)(proj0 + grow * 1440 + 512 + kvh * 64 + ch * 8);
;     }
; #pragma unroll
;     for (int i = 0; i < 2; ++i) {
;       const int c = tid + 256 * i;
;       const int row = c >> 3, ch = c & 7;
;       const int key = (kb + row < LT) ? kb + row : LT - 1;
;       const size_t grow = (size_t)b * LT + key;
;       vreg[i] = MLA ? *(const u32x4*)(kvmla + grow * 1024 + head * 128 + 64 + ch * 8) : *(const u32x4*)(proj0 + grow * 1440 + 640 + kvh * 64 + ch * 8);
;     }
;   };
;   gload(klo);
.LBB0_381:
	s_ashr_i32 s18, s77, 31
	s_lshr_b32 s18, s18, 26
	s_add_i32 s18, s77, s18
	s_lshr_b32 s62, s18, 6
	s_andn2_b32 s18, s18, 63
	s_sub_i32 s18, s77, s18
	s_lshr_b32 s40, s18, 3
	s_and_b32 s79, s18, 7
	s_lshl_b32 s18, s62, 7
	s_sub_i32 s63, 0x2000, s18
	v_add_u32_e32 v160, s63, v115
	v_or_b32_e32 v159, v160, v177
	v_cmp_gt_u32_e64 s[18:19], s3, v159
	s_mul_i32 s58, s40, 0x2010
	s_mul_i32 s40, s79, 0xc0
	v_cndmask_b32_e64 v0, v156, v159, s[18:19]
	v_add_u32_e32 v2, s58, v0
	v_mov_b64_e32 v[0:1], s[34:35]
	v_mad_i64_i32 v[0:1], s[60:61], v2, s76, v[0:1]
	v_lshl_add_u64 v[0:1], v[0:1], 0, s[40:41]
	v_lshl_add_u64 v[0:1], v[0:1], 0, v[108:109]
	global_load_dwordx4 v[64:67], v[0:1], off
	global_load_dwordx4 v[68:71], v[0:1], off offset:32
	global_load_dwordx4 v[72:75], v[0:1], off offset:64
	global_load_dwordx4 v[76:79], v[0:1], off offset:96
	global_load_dwordx4 v[80:83], v[0:1], off offset:128
	global_load_dwordx4 v[84:87], v[0:1], off offset:160
	s_ashr_i32 s59, s58, 31
	v_lshl_add_u64 v[4:5], s[58:59], 0, v[112:113]
	s_and_saveexec_b64 s[60:61], s[8:9]
	s_xor_b64 s[60:61], exec, s[60:61]
	v_lshlrev_b64 v[0:1], 6, v[4:5]
	v_lshl_add_u64 v[0:1], v[124:125], 0, v[0:1]
	v_lshl_add_u64 v[2:3], v[0:1], 0, s[42:43]
	s_or_saveexec_b64 s[60:61], s[60:61]
	v_lshlrev_b32_e32 v0, 1, v114
	s_xor_b64 exec, exec, s[60:61]
	v_lshlrev_b64 v[2:3], 11, v[4:5]
	v_lshl_add_u64 v[2:3], s[38:39], 0, v[2:3]
	s_lshl_b32 s40, s79, 8
	v_lshl_add_u64 v[2:3], v[2:3], 0, s[40:41]
	v_mov_b32_e32 v1, v109
	v_lshl_add_u64 v[2:3], v[2:3], 0, v[0:1]
	s_or_b64 exec, exec, s[60:61]
	global_load_dwordx4 v[88:91], v[2:3], off
	v_lshl_add_u64 v[6:7], s[58:59], 0, v[116:117]
	s_and_saveexec_b64 s[60:61], s[12:13]
	s_xor_b64 s[60:61], exec, s[60:61]
	v_lshlrev_b64 v[2:3], 6, v[6:7]
	v_lshl_add_u64 v[2:3], v[126:127], 0, v[2:3]
	v_lshl_add_u64 v[4:5], v[2:3], 0, s[42:43]
	s_or_saveexec_b64 s[60:61], s[60:61]
	v_lshlrev_b32_e32 v2, 1, v118
	s_xor_b64 exec, exec, s[60:61]
	v_lshlrev_b64 v[4:5], 11, v[6:7]
	v_lshl_add_u64 v[4:5], s[38:39], 0, v[4:5]
	s_lshl_b32 s40, s79, 8
	v_lshl_add_u64 v[4:5], v[4:5], 0, s[40:41]
	v_mov_b32_e32 v3, v109
	v_lshl_add_u64 v[4:5], v[4:5], 0, v[2:3]
	s_or_b64 exec, exec, s[60:61]
	global_load_dwordx4 v[92:95], v[4:5], off
	v_lshl_add_u64 v[8:9], s[58:59], 0, v[120:121]
	s_and_saveexec_b64 s[60:61], s[16:17]
	s_xor_b64 s[60:61], exec, s[60:61]
	v_lshlrev_b64 v[4:5], 6, v[8:9]
	v_lshl_add_u64 v[4:5], v[128:129], 0, v[4:5]
	v_lshl_add_u64 v[6:7], v[4:5], 0, s[42:43]
	s_lshl_b32 s40, s79, 7
	s_or_saveexec_b64 s[60:61], s[60:61]
	v_mov_b64_e32 v[10:11], s[40:41]
	v_lshlrev_b32_e32 v4, 1, v122
	s_xor_b64 exec, exec, s[60:61]
	v_lshlrev_b64 v[6:7], 11, v[8:9]
	v_lshl_add_u64 v[6:7], s[38:39], 0, v[6:7]
	s_lshl_b32 s80, s79, 8
	s_mov_b32 s81, s41
	s_lshl_b32 s40, s79, 7
	v_lshl_add_u64 v[6:7], v[6:7], 0, s[80:81]
	v_mov_b32_e32 v5, v109
	v_lshl_add_u64 v[6:7], v[6:7], 0, v[4:5]
	v_mov_b64_e32 v[10:11], s[40:41]
	s_or_b64 exec, exec, s[60:61]
	global_load_dwordx4 v[96:99], v[6:7], off
	v_lshl_add_u64 v[6:7], s[58:59], 0, v[186:187]
	v_lshlrev_b64 v[6:7], 11, v[6:7]
	v_lshlrev_b64 v[8:9], 1, v[10:11]
	v_lshl_add_u64 v[10:11], s[58:59], 0, v[110:111]
	v_lshl_add_u64 v[6:7], s[38:39], 0, v[6:7]
	v_lshlrev_b64 v[10:11], 11, v[10:11]
	v_lshl_add_u64 v[6:7], v[6:7], 0, v[8:9]
	v_mov_b32_e32 v133, v109
	v_lshl_add_u64 v[10:11], s[38:39], 0, v[10:11]
	v_lshl_add_u64 v[6:7], v[6:7], 0, v[132:133]
	v_lshl_add_u64 v[10:11], v[10:11], 0, v[8:9]
	v_lshl_add_u64 v[10:11], v[10:11], 0, v[132:133]
	global_load_dwordx4 v[100:103], v[6:7], off offset:128
	global_load_dwordx4 v[104:107], v[10:11], off offset:128
	s_sub_i32 s40, 0, s62
	s_lshl_b32 s60, s40, 7
	s_addk_i32 s60, 0x207f
	s_or_b32 s40, s63, 0x7f
	v_lshl_add_u64 v[6:7], s[38:39], 0, v[8:9]
	v_mov_b32_e32 v1, v109
	v_mov_b32_e32 v3, v109
	v_mov_b32_e32 v5, v109
	s_min_u32 s60, s60, 0x200f
	v_mov_b32_e32 v14, v109
	v_mov_b32_e32 v15, v109
	s_min_u32 s40, s40, 0x200f
	v_lshl_add_u64 v[134:135], v[6:7], 0, v[0:1]
	v_lshl_add_u64 v[136:137], v[6:7], 0, v[2:3]
	v_lshl_add_u64 v[138:139], v[6:7], 0, v[4:5]
	v_lshl_add_u64 v[140:141], v[6:7], 0, v[132:133]
	s_and_b32 s80, s60, 0x3fc0
	v_mov_b32_e32 v0, v109
	v_mov_b32_e32 v2, v109
	v_mov_b32_e32 v4, v109
	v_mov_b32_e32 v6, v109
	v_mov_b32_e32 v7, v109
	v_mov_b32_e32 v8, v109
	v_mov_b32_e32 v9, v109
	v_mov_b32_e32 v10, v109
	v_mov_b32_e32 v11, v109
	v_mov_b32_e32 v12, v109
	v_mov_b32_e32 v13, v109
	v_mov_b64_e32 v[30:31], v[14:15]
	s_lshr_b32 s40, s40, 6
	v_or_b32_e32 v161, 31, v160
	s_add_i32 s80, s80, 64
	s_mov_b32 s81, 0
	v_mov_b32_e32 v133, 0xf149f2ca
	v_mov_b32_e32 v162, 0
	v_mov_b64_e32 v[28:29], v[12:13]
	v_mov_b64_e32 v[26:27], v[10:11]
	v_mov_b64_e32 v[24:25], v[8:9]
	v_mov_b64_e32 v[22:23], v[6:7]
	v_mov_b64_e32 v[20:21], v[4:5]
	v_mov_b64_e32 v[18:19], v[2:3]
	v_mov_b64_e32 v[16:17], v[0:1]
	s_mov_b32 s82, 0
	s_mov_b32 s91, 0
	s_branch .LBB0_398

; template <bool MLA>
; DI void attn_task(const Params& p, char* smem, int b, int head, int qt) {
;     ...
;   auto gload = [&](int kt_) {
;     const int kb = kt_ * 64;
; #pragma unroll
;     for (int i = 0; i < NKC; ++i) {
;       const int c = tid + 256 * i;
;       const int row = c / (DQK / 8), ch = c % (DQK / 8);
;       const int key = (kb + row < LT) ? kb + row : LT - 1;
;       const size_t grow = (size_t)b * LT + key;
;       if (MLA) kreg[i] = ch < 8 ? *(const u32x4*)(kvmla + grow * 1024 + head * 128 + ch * 8) : *(const u32x4*)(krope + grow * 32 + (ch - 8) * 8);
;       else kreg[i] = *(const u32x4*)(proj0 + grow * 1440 + 512 + kvh * 64 + ch * 8);
;     }
; #pragma unroll
;     for (int i = 0; i < 2; ++i) {
;       const int c = tid + 256 * i;
;       const int row = c >> 3, ch = c & 7;
;       const int key = (kb + row < LT) ? kb + row : LT - 1;
;       const size_t grow = (size_t)b * LT + key;
;       vreg[i] = MLA ? *(const u32x4*)(kvmla + grow * 1024 + head * 128 + 64 + ch * 8) : *(const u32x4*)(proj0 + grow * 1440 + 640 + kvh * 64 + ch * 8);
;     }
;   };
;     ...
;     __syncthreads();
; #pragma unroll
;     for (int i = 0; i < NKC; ++i) {
;       const int c = tid + 256 * i;
;       *(u32x4*)(Ks + (c / (DQK / 8)) * KLD + (c % (DQK / 8)) * 8) = kreg[i];
;     }
; #pragma unroll
;     for (int i = 0; i < 2; ++i) {
;       const int c = tid + 256 * i;
;       *(u32x4*)(Vs + (c >> 3) * VLD + (c & 7) * 8) = vreg[i];
;     }
;     __syncthreads();
;     if (kt < khi) gload(kt + 1);
.LBB0_398:
	s_cmp_ge_u32 s82, s40
	s_waitcnt lgkmcnt(0)
	s_barrier
	s_waitcnt vmcnt(4)
	ds_write_b128 v152, v[88:91]
	s_waitcnt vmcnt(3)
	ds_write_b128 v153, v[92:95]
	s_waitcnt vmcnt(2)
	ds_write_b128 v154, v[96:99]
	s_waitcnt vmcnt(1)
	ds_write_b128 v149, v[100:103] offset:13312
	s_waitcnt vmcnt(0)
	ds_write_b128 v150, v[104:107] offset:13312
	s_waitcnt lgkmcnt(0)
	s_barrier
	s_cbranch_scc1 .LBB0_400
	s_cmp_eq_u32 s91, 0
	s_cbranch_scc1 .Lmy_gl_slow
	s_cmpk_gt_u32 s81, 0x1f90
	s_cbranch_scc1 .Lmy_gl_slow
	v_mov_b32_e32 v200, 0x1000
	v_mov_b32_e32 v201, 0x20000
	v_mov_b32_e32 v203, 0
	s_mov_b32 s92, 0x20000
	s_mov_b32 s93, 0
	v_cndmask_b32_e64 v202, v200, v201, s[6:7]
	v_lshl_add_u64 v[204:205], v[204:205], 0, v[202:203]
	global_load_dwordx4 v[88:91], v[204:205], off
	v_cndmask_b32_e64 v202, v200, v201, s[10:11]
	v_lshl_add_u64 v[206:207], v[206:207], 0, v[202:203]
	global_load_dwordx4 v[92:95], v[206:207], off
	v_cndmask_b32_e64 v202, v200, v201, s[14:15]
	v_lshl_add_u64 v[208:209], v[208:209], 0, v[202:203]
	global_load_dwordx4 v[96:99], v[208:209], off
	v_lshl_add_u64 v[210:211], v[210:211], 0, s[92:93]
	global_load_dwordx4 v[100:103], v[210:211], off offset:128
	v_lshl_add_u64 v[212:213], v[212:213], 0, s[92:93]
	global_load_dwordx4 v[104:107], v[212:213], off offset:128
	s_branch .LBB0_400
.Lmy_gl_slow:
	v_add_u32_e32 v32, s81, v146
	v_min_i32_e32 v32, 0x200f, v32
	v_ashrrev_i32_e32 v33, 31, v32
	v_lshl_add_u64 v[32:33], v[32:33], 0, s[58:59]
	v_lshlrev_b64 v[34:35], 11, v[32:33]
	v_lshlrev_b64 v[32:33], 6, v[32:33]
	v_lshl_add_u64 v[32:33], v[124:125], 0, v[32:33]
	v_lshl_add_u64 v[34:35], v[134:135], 0, v[34:35]
	v_lshl_add_u64 v[32:33], v[32:33], 0, s[42:43]
	v_cndmask_b32_e64 v33, v33, v35, s[6:7]
	v_cndmask_b32_e64 v32, v32, v34, s[6:7]
	global_load_dwordx4 v[88:91], v[32:33], off
	v_mov_b32_e32 v204, v32
	v_mov_b32_e32 v205, v33
	v_add_u32_e32 v32, s81, v145
	v_min_i32_e32 v32, 0x200f, v32
	v_ashrrev_i32_e32 v33, 31, v32
	v_lshl_add_u64 v[32:33], v[32:33], 0, s[58:59]
	v_lshlrev_b64 v[34:35], 11, v[32:33]
	v_lshlrev_b64 v[32:33], 6, v[32:33]
	v_lshl_add_u64 v[32:33], v[126:127], 0, v[32:33]
	v_lshl_add_u64 v[34:35], v[136:137], 0, v[34:35]
	v_lshl_add_u64 v[32:33], v[32:33], 0, s[42:43]
	v_cndmask_b32_e64 v33, v33, v35, s[10:11]
	v_cndmask_b32_e64 v32, v32, v34, s[10:11]
	global_load_dwordx4 v[92:95], v[32:33], off
	v_mov_b32_e32 v206, v32
	v_mov_b32_e32 v207, v33
	v_add_u32_e32 v32, s81, v144
	v_min_i32_e32 v32, 0x200f, v32
	v_ashrrev_i32_e32 v33, 31, v32
	v_lshl_add_u64 v[32:33], v[32:33], 0, s[58:59]
	v_lshlrev_b64 v[34:35], 11, v[32:33]
	v_lshlrev_b64 v[32:33], 6, v[32:33]
	v_lshl_add_u64 v[32:33], v[128:129], 0, v[32:33]
	v_lshl_add_u64 v[34:35], v[138:139], 0, v[34:35]
	v_lshl_add_u64 v[32:33], v[32:33], 0, s[42:43]
	v_cndmask_b32_e64 v33, v33, v35, s[14:15]
	v_cndmask_b32_e64 v32, v32, v34, s[14:15]
	global_load_dwordx4 v[96:99], v[32:33], off
	v_mov_b32_e32 v208, v32
	v_mov_b32_e32 v209, v33
	v_add_u32_e32 v32, s81, v143
	v_min_i32_e32 v32, 0x200f, v32
	v_add_u32_e32 v34, s81, v142
	v_ashrrev_i32_e32 v33, 31, v32
	v_min_i32_e32 v34, 0x200f, v34
	v_lshl_add_u64 v[32:33], v[32:33], 0, s[58:59]
	v_ashrrev_i32_e32 v35, 31, v34
	v_lshlrev_b64 v[32:33], 11, v[32:33]
	v_lshl_add_u64 v[34:35], v[34:35], 0, s[58:59]
	v_lshl_add_u64 v[32:33], v[140:141], 0, v[32:33]
	v_lshlrev_b64 v[34:35], 11, v[34:35]
	v_lshl_add_u64 v[34:35], v[140:141], 0, v[34:35]
	global_load_dwordx4 v[100:103], v[32:33], off offset:128
	global_load_dwordx4 v[104:107], v[34:35], off offset:128
	v_mov_b32_e32 v210, v32
	v_mov_b32_e32 v211, v33
	v_mov_b32_e32 v212, v34
	v_mov_b32_e32 v213, v35
	s_mov_b32 s91, 1
